# gate/up #1 K-loop: no VALU in load segments (saddr-form LDS-DMA with scalar base math, pre-biased B read base)
# baseline (speedup 1.0000x reference)
; #define PG8_STAGE(bufoff, gbase, voff) do { _Pragma("unroll") for (int _i = 0; _i < 2; ++_i) \
;         __builtin_amdgcn_global_load_lds((const unsigned*)((const char*)(gbase) + (voff)[_i]), (LAS unsigned*)(lds + (bufoff) + ldsw + _i * 8192), 16, 0, 0); } while (0)
; #define PG8_WAIT_V(n) asm volatile("s_waitcnt vmcnt(" #n ")" ::: "memory")
; #define PG8_BAR __builtin_amdgcn_s_barrier()
; template <class Epi>
; __device__ __forceinline__ void gemm_phase(LAS unsigned char* lds, const Gemm g, const StaticOrder& S, const Epi& E, const int tid) {
;     ...
;     const int aoff = lds_byte(wr * 64 + fr, fq * 8), boff = lds_byte(wc * 32 + fr, fq * 8);
;     ...
;     Unit cur, nxt; int ui = 0;
;     if (!S.next(0, cur)) return;
;     f32x4 acc[2][2][4][2];
; #pragma unroll
;     for (int a = 0; a < 2; ++a)
; #pragma unroll
;         for (int b = 0; b < 2; ++b)
; #pragma unroll
;             for (int m = 0; m < 4; ++m)
; #pragma unroll
;                 for (int n = 0; n < 2; ++n) acc[a][b][m][n] = (f32x4){0.f, 0.f, 0.f, 0.f};
;     bf16x8 At[4][2], B0[2][2], B1[2][2];
;     const char* cA = PG8_APTR(cur); const char* cB = PG8_BPTR(cur);
;     PG8_STAGE(PG8_SB(0, 0), cB, voffB); PG8_STAGE(PG8_SB(0, 1), cB + hsB, voffB); PG8_STAGE(PG8_SA(0, 0), cA, voffA); PG8_STAGE(PG8_SA(0, 1), cA + hsA, voffA);
;     if (wr == 1) PG8_BAR;
;     PG8_WAIT_V(2); PG8_BAR;
;     PG8_STAGE(PG8_SB(1, 0), cB + kstep, voffB); PG8_STAGE(PG8_SA(1, 0), cA + kstep, voffA); PG8_STAGE(PG8_SB(1, 1), cB + hsB + kstep, voffB);
;     PG8_WAIT_V(6); PG8_BAR;
.LBB0_155:
	v_mov_b32_e32 v133, v169
	v_lshl_add_u64 v[6:7], s[0:1], 0, v[168:169]
	v_readlane_b32 s34, v254, 19
	v_lshrrev_b32_e32 v14, 1, v214
	v_and_b32_e32 v15, 15, v214
	s_lshl_b32 s11, s11, 5
	v_mov_b32_e32 v129, v169
	v_lshl_add_u64 v[8:9], s[0:1], 0, v[132:133]
	v_readlane_b32 s35, v254, 20
	v_and_b32_e32 v14, 24, v14
	v_lshlrev_b32_e32 v16, 6, v15
	v_lshlrev_b32_e32 v17, 2, v214
	s_and_b32 s14, s11, 0x60
	s_add_i32 m0, s42, 0x18000
	v_lshl_add_u64 v[6:7], v[6:7], 0, s[28:29]
	v_mov_b32_e32 v131, v169
	v_lshl_add_u64 v[10:11], s[34:35], 0, v[128:129]
	v_lshl_or_b32 v16, v14, 1, v16
	v_and_b32_e32 v17, 32, v17
	v_lshl_or_b32 v142, s12, 6, v15
	s_lshl_b32 s12, s12, 13
	s_lshl_b32 s11, s14, 7
	s_waitcnt vmcnt(2)
	s_barrier
	global_load_lds_dwordx4 v[6:7], off
	v_lshl_add_u64 v[6:7], v[8:9], 0, s[28:29]
	s_add_i32 m0, s42, 0x1a000
	s_add_i32 s46, s42, 0x8000
	s_add_i32 s47, s42, 0xa000
	v_lshl_add_u64 v[12:13], s[34:35], 0, v[130:131]
	v_bitop3_b32 v15, v16, s12, v17 bitop3:0xde
	global_load_lds_dwordx4 v[6:7], off
	v_lshl_add_u64 v[6:7], v[10:11], 0, s[28:29]
	s_mov_b32 m0, s46
	s_add_u32 s12, s0, 0x80080
	global_load_lds_dwordx4 v[6:7], off
	v_lshl_add_u64 v[6:7], v[12:13], 0, s[28:29]
	s_mov_b32 m0, s47
	s_addc_u32 s13, s1, 0
	global_load_lds_dwordx4 v[6:7], off
	s_add_i32 m0, s42, 0x1c000
	v_lshl_add_u64 v[6:7], s[12:13], 0, v[168:169]
	global_load_lds_dwordx4 v[6:7], off
	v_lshl_add_u64 v[6:7], s[12:13], 0, v[132:133]
	s_add_i32 m0, s42, 0x1e000
	s_cmpk_lt_u32 s10, 0x100
	global_load_lds_dwordx4 v[6:7], off
	v_lshlrev_b32_e32 v6, 15, v0
	v_and_b32_e32 v6, 0xffff0000, v6
	v_lshl_add_u32 v1, v1, 12, v6
	v_and_b32_e32 v0, 1, v0
	v_lshl_or_b32 v0, v0, 6, v1
	v_lshl_add_u32 v134, v2, 1, v0
	v_lshlrev_b32_e32 v0, 15, v3
	v_and_b32_e32 v0, 0xffff0000, v0
	s_waitcnt vmcnt(6)
	v_lshl_add_u32 v0, v4, 12, v0
	v_and_b32_e32 v1, 1, v3
	v_lshl_or_b32 v0, v1, 6, v0
	v_readlane_b32 s12, v254, 17
	v_bitop3_b32 v143, s11, v16, v17 bitop3:0xf6
	s_cselect_b64 s[10:11], -1, 0
	v_or_b32_e32 v144, s14, v14
	v_mov_b32_e32 v135, v169
	v_lshl_add_u32 v136, v5, 1, v0
	v_mov_b32_e32 v137, v169
	s_mov_b32 s48, 0
	v_add_u32_e32 v145, 0, v15
	v_add_u32_e32 v171, 0x10000, v143
	v_readlane_b32 s49, v254, 14
	s_mov_b32 s52, s12
	s_barrier
	v_readlane_b32 s13, v254, 18
	s_branch .LBB0_158

; #define PG8_STAGE(bufoff, gbase, voff) do { _Pragma("unroll") for (int _i = 0; _i < 2; ++_i) \
;         __builtin_amdgcn_global_load_lds((const unsigned*)((const char*)(gbase) + (voff)[_i]), (LAS unsigned*)(lds + (bufoff) + ldsw + _i * 8192), 16, 0, 0); } while (0)
; #define PG8_LDA(dst, b, h) do { _Pragma("unroll") for (int m = 0; m < 4; ++m) _Pragma("unroll") for (int k = 0; k < 2; ++k) dst[m][k] = *(const LAS bf16x8*)(lds + PG8_SA(b, h) + aoff + m * 2048 + k * 1024); } while (0)
; #define PG8_LDB(dst, b, h) do { _Pragma("unroll") for (int n = 0; n < 2; ++n) _Pragma("unroll") for (int k = 0; k < 2; ++k) dst[n][k] = *(const LAS bf16x8*)(lds + PG8_SB(b, h) + boff + n * 2048 + k * 1024); } while (0)
; #define PG8_MMA(ai, bj, At, Bt) do { __builtin_amdgcn_s_setprio(1); _Pragma("unroll") for (int m = 0; m < 4; ++m) _Pragma("unroll") for (int n = 0; n < 2; ++n) _Pragma("unroll") for (int k = 0; k < 2; ++k) \
;         acc[ai][bj][m][n] = __builtin_amdgcn_mfma_f32_16x16x32_bf16(Bt[n][k], At[m][k], acc[ai][bj][m][n], 0, 0, 0); __builtin_amdgcn_s_setprio(0); } while (0)
; #define PG8_WAIT_V(n) asm volatile("s_waitcnt vmcnt(" #n ")" ::: "memory")
; #define PG8_WAIT_L(n) asm volatile("s_waitcnt lgkmcnt(" #n ")" ::: "memory")
; #define PG8_BAR __builtin_amdgcn_s_barrier()
; #define PG8_SCHED __builtin_amdgcn_sched_barrier(0)
; template <class Epi>
; __device__ __forceinline__ void gemm_phase(LAS unsigned char* lds, const Gemm g, const StaticOrder& S, const Epi& E, const int tid) {
;     ...
;         for (int t = 0; t < nt; t += 2) {
;             const bool last = (t == nt - 2);
;             const char* a1 = cA + (size_t)(t + 1) * kstep;
;             const char* a2 = last ? nA : cA + (size_t)(t + 2) * kstep; const char* b2 = last ? nB : cB + (size_t)(t + 2) * kstep;
;             const char* a3 = a2 + kstep; const char* b3 = b2 + kstep;
;             PG8_LDB(B0, 0, 0); PG8_LDB(B1, 0, 1); PG8_SCHED; PG8_LDA(At, 0, 0); PG8_STAGE(PG8_SA(1, 1), a1 + hsA, voffA);
;             PG8_WAIT_V(8); PG8_WAIT_L(0); PG8_BAR; PG8_MMA(0, 0, At, B0); PG8_MMA(0, 1, At, B1); PG8_BAR; PG8_SCHED;
;             PG8_LDA(At, 0, 1); PG8_STAGE(PG8_SB(0, 0), b2, voffB); PG8_STAGE(PG8_SB(0, 1), b2 + hsB, voffB); PG8_STAGE(PG8_SA(0, 0), a2, voffA);
;             PG8_WAIT_V(8); PG8_WAIT_L(0); PG8_BAR; PG8_MMA(1, 0, At, B0); PG8_MMA(1, 1, At, B1); PG8_BAR; PG8_SCHED;
.LBB0_161:
	s_add_u32 s0, s34, 0xfff80080
	s_addc_u32 s1, s35, -1
	s_add_i32 s24, 0, 0x10000
	s_cmp_eq_u32 s59, 28
	s_cselect_b32 s39, s15, s1
	s_cselect_b32 s38, s53, s0
	s_cselect_b32 s1, s13, s58
	s_cselect_b32 s0, s56, s57
	s_add_i32 s25, 0, 0x14000
	ds_read_b128 v[138:141], v171
	ds_read_b128 v[146:149], v171 offset:1024
	ds_read_b128 v[150:153], v171 offset:2048
	ds_read_b128 v[154:157], v171 offset:3072
	ds_read_b128 v[158:161], v171 offset:16384
	ds_read_b128 v[162:165], v171 offset:17408
	ds_read_b128 v[184:187], v171 offset:18432
	ds_read_b128 v[188:191], v171 offset:19456
	s_add_i32 m0, s42, 0xc000
	ds_read_b128 v[192:195], v145
	ds_read_b128 v[196:199], v145 offset:1024
	ds_read_b128 v[200:203], v145 offset:2048
	ds_read_b128 v[204:207], v145 offset:3072
	ds_read_b128 v[208:211], v145 offset:4096
	ds_read_b128 v[230:233], v145 offset:5120
	ds_read_b128 v[234:237], v145 offset:6144
	ds_read_b128 v[238:241], v145 offset:7168
	global_load_lds_dwordx4 v134, s[34:35]
	s_add_i32 m0, s42, 0xe000
	s_nop 0
	global_load_lds_dwordx4 v136, s[34:35]
	s_waitcnt vmcnt(8)
	s_waitcnt lgkmcnt(0)
	s_barrier
	s_setprio 1
	s_waitcnt lgkmcnt(0)
	v_mfma_f32_16x16x32_bf16 v[124:127], v[138:141], v[192:195], v[124:127]
	v_mfma_f32_16x16x32_bf16 v[116:119], v[150:153], v[192:195], v[116:119]
	v_mfma_f32_16x16x32_bf16 v[108:111], v[138:141], v[200:203], v[108:111]
	v_mfma_f32_16x16x32_bf16 v[100:103], v[150:153], v[200:203], v[100:103]
	v_mfma_f32_16x16x32_bf16 v[92:95], v[138:141], v[208:211], v[92:95]
	v_mfma_f32_16x16x32_bf16 v[84:87], v[150:153], v[208:211], v[84:87]
	v_mfma_f32_16x16x32_bf16 v[76:79], v[138:141], v[234:237], v[76:79]
	v_mfma_f32_16x16x32_bf16 v[68:71], v[150:153], v[234:237], v[68:71]
	v_mfma_f32_16x16x32_bf16 v[124:127], v[146:149], v[196:199], v[124:127]
	v_mfma_f32_16x16x32_bf16 v[116:119], v[154:157], v[196:199], v[116:119]
	v_mfma_f32_16x16x32_bf16 v[108:111], v[146:149], v[204:207], v[108:111]
	v_mfma_f32_16x16x32_bf16 v[100:103], v[154:157], v[204:207], v[100:103]
	v_mfma_f32_16x16x32_bf16 v[92:95], v[146:149], v[230:233], v[92:95]
	v_mfma_f32_16x16x32_bf16 v[84:87], v[154:157], v[230:233], v[84:87]
	v_mfma_f32_16x16x32_bf16 v[76:79], v[146:149], v[238:241], v[76:79]
	v_mfma_f32_16x16x32_bf16 v[68:71], v[154:157], v[238:241], v[68:71]
	s_setprio 0
	s_setprio 1
	v_mfma_f32_16x16x32_bf16 v[120:123], v[158:161], v[192:195], v[120:123]
	v_mfma_f32_16x16x32_bf16 v[112:115], v[184:187], v[192:195], v[112:115]
	v_mfma_f32_16x16x32_bf16 v[104:107], v[158:161], v[200:203], v[104:107]
	v_mfma_f32_16x16x32_bf16 v[96:99], v[184:187], v[200:203], v[96:99]
	v_mfma_f32_16x16x32_bf16 v[88:91], v[158:161], v[208:211], v[88:91]
	v_mfma_f32_16x16x32_bf16 v[80:83], v[184:187], v[208:211], v[80:83]
	v_mfma_f32_16x16x32_bf16 v[72:75], v[158:161], v[234:237], v[72:75]
	v_mfma_f32_16x16x32_bf16 v[64:67], v[184:187], v[234:237], v[64:67]
	v_mfma_f32_16x16x32_bf16 v[120:123], v[162:165], v[196:199], v[120:123]
	v_mfma_f32_16x16x32_bf16 v[112:115], v[188:191], v[196:199], v[112:115]
	v_mfma_f32_16x16x32_bf16 v[104:107], v[162:165], v[204:207], v[104:107]
	v_mfma_f32_16x16x32_bf16 v[96:99], v[188:191], v[204:207], v[96:99]
	v_mfma_f32_16x16x32_bf16 v[88:91], v[162:165], v[230:233], v[88:91]
	v_mfma_f32_16x16x32_bf16 v[80:83], v[188:191], v[230:233], v[80:83]
	v_mfma_f32_16x16x32_bf16 v[72:75], v[162:165], v[238:241], v[72:75]
	v_mfma_f32_16x16x32_bf16 v[64:67], v[188:191], v[238:241], v[64:67]
	s_setprio 0
	s_barrier
	s_add_i32 s24, s24, s27
	s_mov_b32 m0, s24
	ds_read_b128 v[192:195], v145 offset:16384
	ds_read_b128 v[196:199], v145 offset:17408
	ds_read_b128 v[200:203], v145 offset:18432
	ds_read_b128 v[204:207], v145 offset:19456
	ds_read_b128 v[208:211], v145 offset:20480
	ds_read_b128 v[230:233], v145 offset:21504
	ds_read_b128 v[234:237], v145 offset:22528
	ds_read_b128 v[238:241], v145 offset:23552
	global_load_lds_dwordx4 v168, s[0:1]
	s_add_i32 m0, s24, 0x2000
	s_add_u32 s68, s0, 0x80000
	s_addc_u32 s69, s1, 0
	s_add_i32 s24, s25, s27
	global_load_lds_dwordx4 v132, s[0:1]
	s_mov_b32 m0, s24
	s_nop 0
	global_load_lds_dwordx4 v168, s[68:69]
	s_add_i32 m0, s24, 0x2000
	s_nop 0
	global_load_lds_dwordx4 v132, s[68:69]
	s_mov_b32 m0, s42
	s_nop 0
	global_load_lds_dwordx4 v128, s[38:39]
	s_mov_b32 m0, s43
	s_nop 0
	global_load_lds_dwordx4 v130, s[38:39]
	s_waitcnt vmcnt(8)
	s_waitcnt lgkmcnt(0)
	s_barrier
	s_setprio 1
	s_waitcnt lgkmcnt(0)
	v_mfma_f32_16x16x32_bf16 v[60:63], v[138:141], v[192:195], v[60:63]
	v_mfma_f32_16x16x32_bf16 v[52:55], v[150:153], v[192:195], v[52:55]
	v_mfma_f32_16x16x32_bf16 v[44:47], v[138:141], v[200:203], v[44:47]
	v_mfma_f32_16x16x32_bf16 v[36:39], v[150:153], v[200:203], v[36:39]
	v_mfma_f32_16x16x32_bf16 v[28:31], v[138:141], v[208:211], v[28:31]
	v_mfma_f32_16x16x32_bf16 v[20:23], v[150:153], v[208:211], v[20:23]
	v_mfma_f32_16x16x32_bf16 v[12:15], v[138:141], v[234:237], v[12:15]
	v_mfma_f32_16x16x32_bf16 v[4:7], v[150:153], v[234:237], v[4:7]
	v_mfma_f32_16x16x32_bf16 v[60:63], v[146:149], v[196:199], v[60:63]
	v_mfma_f32_16x16x32_bf16 v[52:55], v[154:157], v[196:199], v[52:55]
	v_mfma_f32_16x16x32_bf16 v[44:47], v[146:149], v[204:207], v[44:47]
	v_mfma_f32_16x16x32_bf16 v[36:39], v[154:157], v[204:207], v[36:39]
	v_mfma_f32_16x16x32_bf16 v[28:31], v[146:149], v[230:233], v[28:31]
	v_mfma_f32_16x16x32_bf16 v[20:23], v[154:157], v[230:233], v[20:23]
	v_mfma_f32_16x16x32_bf16 v[12:15], v[146:149], v[238:241], v[12:15]
	v_mfma_f32_16x16x32_bf16 v[4:7], v[154:157], v[238:241], v[4:7]
	s_setprio 0
	s_setprio 1
	v_mfma_f32_16x16x32_bf16 v[56:59], v[158:161], v[192:195], v[56:59]
	v_mfma_f32_16x16x32_bf16 v[48:51], v[184:187], v[192:195], v[48:51]
	v_mfma_f32_16x16x32_bf16 v[40:43], v[158:161], v[200:203], v[40:43]
	v_mfma_f32_16x16x32_bf16 v[32:35], v[184:187], v[200:203], v[32:35]
	v_mfma_f32_16x16x32_bf16 v[24:27], v[158:161], v[208:211], v[24:27]
	v_mfma_f32_16x16x32_bf16 v[16:19], v[184:187], v[208:211], v[16:19]
	v_mfma_f32_16x16x32_bf16 v[8:11], v[158:161], v[234:237], v[8:11]
	v_mfma_f32_16x16x32_bf16 v[0:3], v[184:187], v[234:237], v[0:3]
	v_mfma_f32_16x16x32_bf16 v[56:59], v[162:165], v[196:199], v[56:59]
	v_mfma_f32_16x16x32_bf16 v[48:51], v[188:191], v[196:199], v[48:51]
	v_mfma_f32_16x16x32_bf16 v[40:43], v[162:165], v[204:207], v[40:43]
	v_mfma_f32_16x16x32_bf16 v[32:35], v[188:191], v[204:207], v[32:35]
	v_mfma_f32_16x16x32_bf16 v[24:27], v[162:165], v[230:233], v[24:27]
	v_mfma_f32_16x16x32_bf16 v[16:19], v[188:191], v[230:233], v[16:19]
	v_mfma_f32_16x16x32_bf16 v[8:11], v[162:165], v[238:241], v[8:11]
	v_mfma_f32_16x16x32_bf16 v[0:3], v[188:191], v[238:241], v[0:3]
	s_setprio 0
	s_barrier
; #define PG8_STAGE(bufoff, gbase, voff) do { _Pragma("unroll") for (int _i = 0; _i < 2; ++_i) \
;         __builtin_amdgcn_global_load_lds((const unsigned*)((const char*)(gbase) + (voff)[_i]), (LAS unsigned*)(lds + (bufoff) + ldsw + _i * 8192), 16, 0, 0); } while (0)
; #define PG8_LDA(dst, b, h) do { _Pragma("unroll") for (int m = 0; m < 4; ++m) _Pragma("unroll") for (int k = 0; k < 2; ++k) dst[m][k] = *(const LAS bf16x8*)(lds + PG8_SA(b, h) + aoff + m * 2048 + k * 1024); } while (0)
; #define PG8_LDB(dst, b, h) do { _Pragma("unroll") for (int n = 0; n < 2; ++n) _Pragma("unroll") for (int k = 0; k < 2; ++k) dst[n][k] = *(const LAS bf16x8*)(lds + PG8_SB(b, h) + boff + n * 2048 + k * 1024); } while (0)
; #define PG8_MMA(ai, bj, At, Bt) do { __builtin_amdgcn_s_setprio(1); _Pragma("unroll") for (int m = 0; m < 4; ++m) _Pragma("unroll") for (int n = 0; n < 2; ++n) _Pragma("unroll") for (int k = 0; k < 2; ++k) \
;         acc[ai][bj][m][n] = __builtin_amdgcn_mfma_f32_16x16x32_bf16(Bt[n][k], At[m][k], acc[ai][bj][m][n], 0, 0, 0); __builtin_amdgcn_s_setprio(0); } while (0)
; #define PG8_WAIT_V(n) asm volatile("s_waitcnt vmcnt(" #n ")" ::: "memory")
; #define PG8_WAIT_L(n) asm volatile("s_waitcnt lgkmcnt(" #n ")" ::: "memory")
; #define PG8_BAR __builtin_amdgcn_s_barrier()
; #define PG8_SCHED __builtin_amdgcn_sched_barrier(0)
; template <class Epi>
; __device__ __forceinline__ void gemm_phase(LAS unsigned char* lds, const Gemm g, const StaticOrder& S, const Epi& E, const int tid) {
;     ...
;             PG8_WAIT_V(8); PG8_WAIT_L(0); PG8_BAR; PG8_MMA(1, 0, At, B0); PG8_MMA(1, 1, At, B1); PG8_BAR; PG8_SCHED;
;             PG8_LDB(B0, 1, 0); PG8_LDB(B1, 1, 1); PG8_SCHED; PG8_LDA(At, 1, 0); PG8_STAGE(PG8_SA(0, 1), a2 + hsA, voffA);
;             PG8_WAIT_V(8); PG8_WAIT_L(0); PG8_BAR; PG8_MMA(0, 0, At, B0); PG8_MMA(0, 1, At, B1); PG8_BAR; PG8_SCHED;
;             PG8_LDA(At, 1, 1); PG8_STAGE(PG8_SB(1, 0), b3, voffB); PG8_STAGE(PG8_SB(1, 1), b3 + hsB, voffB); PG8_STAGE(PG8_SA(1, 0), a3, voffA);
;             PG8_WAIT_V(8); PG8_WAIT_L(0); PG8_BAR; PG8_MMA(1, 0, At, B0); PG8_MMA(1, 1, At, B1); PG8_BAR; PG8_SCHED;
;         }
;         if (wr == 0) PG8_BAR;
	s_add_i32 s24, 0, 0x18000
	s_add_i32 s25, 0, 0x1c000
	ds_read_b128 v[138:141], v171 offset:32768
	ds_read_b128 v[146:149], v171 offset:33792
	ds_read_b128 v[150:153], v171 offset:34816
	ds_read_b128 v[154:157], v171 offset:35840
	ds_read_b128 v[158:161], v171 offset:49152
	ds_read_b128 v[162:165], v171 offset:50176
	ds_read_b128 v[184:187], v171 offset:51200
	ds_read_b128 v[188:191], v171 offset:52224
	s_add_u32 s38, s38, 0x80000
	s_addc_u32 s39, s39, 0
	s_mov_b32 m0, s44
	ds_read_b128 v[192:195], v145 offset:32768
	ds_read_b128 v[196:199], v145 offset:33792
	ds_read_b128 v[200:203], v145 offset:34816
	ds_read_b128 v[204:207], v145 offset:35840
	ds_read_b128 v[208:211], v145 offset:36864
	ds_read_b128 v[230:233], v145 offset:37888
	ds_read_b128 v[234:237], v145 offset:38912
	ds_read_b128 v[238:241], v145 offset:39936
	global_load_lds_dwordx4 v128, s[38:39]
	s_mov_b32 m0, s45
	s_nop 0
	global_load_lds_dwordx4 v130, s[38:39]
	s_waitcnt vmcnt(8)
	s_waitcnt lgkmcnt(0)
	s_barrier
	s_setprio 1
	s_waitcnt lgkmcnt(0)
	v_mfma_f32_16x16x32_bf16 v[124:127], v[138:141], v[192:195], v[124:127]
	v_mfma_f32_16x16x32_bf16 v[116:119], v[150:153], v[192:195], v[116:119]
	v_mfma_f32_16x16x32_bf16 v[108:111], v[138:141], v[200:203], v[108:111]
	v_mfma_f32_16x16x32_bf16 v[100:103], v[150:153], v[200:203], v[100:103]
	v_mfma_f32_16x16x32_bf16 v[92:95], v[138:141], v[208:211], v[92:95]
	v_mfma_f32_16x16x32_bf16 v[84:87], v[150:153], v[208:211], v[84:87]
	v_mfma_f32_16x16x32_bf16 v[76:79], v[138:141], v[234:237], v[76:79]
	v_mfma_f32_16x16x32_bf16 v[68:71], v[150:153], v[234:237], v[68:71]
	v_mfma_f32_16x16x32_bf16 v[124:127], v[146:149], v[196:199], v[124:127]
	v_mfma_f32_16x16x32_bf16 v[116:119], v[154:157], v[196:199], v[116:119]
	v_mfma_f32_16x16x32_bf16 v[108:111], v[146:149], v[204:207], v[108:111]
	v_mfma_f32_16x16x32_bf16 v[100:103], v[154:157], v[204:207], v[100:103]
	v_mfma_f32_16x16x32_bf16 v[92:95], v[146:149], v[230:233], v[92:95]
	v_mfma_f32_16x16x32_bf16 v[84:87], v[154:157], v[230:233], v[84:87]
	v_mfma_f32_16x16x32_bf16 v[76:79], v[146:149], v[238:241], v[76:79]
	v_mfma_f32_16x16x32_bf16 v[68:71], v[154:157], v[238:241], v[68:71]
	s_setprio 0
	s_setprio 1
	v_mfma_f32_16x16x32_bf16 v[120:123], v[158:161], v[192:195], v[120:123]
	v_mfma_f32_16x16x32_bf16 v[112:115], v[184:187], v[192:195], v[112:115]
	v_mfma_f32_16x16x32_bf16 v[104:107], v[158:161], v[200:203], v[104:107]
	v_mfma_f32_16x16x32_bf16 v[96:99], v[184:187], v[200:203], v[96:99]
	v_mfma_f32_16x16x32_bf16 v[88:91], v[158:161], v[208:211], v[88:91]
	v_mfma_f32_16x16x32_bf16 v[80:83], v[184:187], v[208:211], v[80:83]
	v_mfma_f32_16x16x32_bf16 v[72:75], v[158:161], v[234:237], v[72:75]
	v_mfma_f32_16x16x32_bf16 v[64:67], v[184:187], v[234:237], v[64:67]
	v_mfma_f32_16x16x32_bf16 v[120:123], v[162:165], v[196:199], v[120:123]
	v_mfma_f32_16x16x32_bf16 v[112:115], v[188:191], v[196:199], v[112:115]
	v_mfma_f32_16x16x32_bf16 v[104:107], v[162:165], v[204:207], v[104:107]
	v_mfma_f32_16x16x32_bf16 v[96:99], v[188:191], v[204:207], v[96:99]
	v_mfma_f32_16x16x32_bf16 v[88:91], v[162:165], v[230:233], v[88:91]
	v_mfma_f32_16x16x32_bf16 v[80:83], v[188:191], v[230:233], v[80:83]
	v_mfma_f32_16x16x32_bf16 v[72:75], v[162:165], v[238:241], v[72:75]
	v_mfma_f32_16x16x32_bf16 v[64:67], v[188:191], v[238:241], v[64:67]
	s_setprio 0
	s_barrier
	s_add_i32 s24, s24, s27
	s_add_u32 s100, s0, 0x80
	s_addc_u32 s101, s1, 0
	s_mov_b32 m0, s24
	ds_read_b128 v[192:195], v145 offset:49152
	ds_read_b128 v[196:199], v145 offset:50176
	ds_read_b128 v[200:203], v145 offset:51200
	ds_read_b128 v[204:207], v145 offset:52224
	ds_read_b128 v[208:211], v145 offset:53248
	ds_read_b128 v[230:233], v145 offset:54272
	ds_read_b128 v[234:237], v145 offset:55296
	ds_read_b128 v[238:241], v145 offset:56320
	global_load_lds_dwordx4 v168, s[100:101]
	s_add_i32 m0, s24, 0x2000
	s_add_u32 s0, s0, 0x80080
	s_addc_u32 s1, s1, 0
	s_add_i32 s24, s25, s27
	global_load_lds_dwordx4 v132, s[100:101]
	s_mov_b32 m0, s24
	s_nop 0
	global_load_lds_dwordx4 v168, s[0:1]
	s_add_i32 m0, s24, 0x2000
	s_nop 0
	global_load_lds_dwordx4 v132, s[0:1]
	s_add_u32 s100, s38, 0xfff80080
	s_addc_u32 s101, s39, -1
	s_mov_b32 m0, s46
	s_nop 0
	global_load_lds_dwordx4 v128, s[100:101]
	s_mov_b32 m0, s47
	s_nop 0
	global_load_lds_dwordx4 v130, s[100:101]
	s_waitcnt vmcnt(8)
	s_waitcnt lgkmcnt(0)
	s_barrier
	s_setprio 1
	s_waitcnt lgkmcnt(0)
	v_mfma_f32_16x16x32_bf16 v[60:63], v[138:141], v[192:195], v[60:63]
	v_mfma_f32_16x16x32_bf16 v[52:55], v[150:153], v[192:195], v[52:55]
	v_mfma_f32_16x16x32_bf16 v[44:47], v[138:141], v[200:203], v[44:47]
	v_mfma_f32_16x16x32_bf16 v[36:39], v[150:153], v[200:203], v[36:39]
	v_mfma_f32_16x16x32_bf16 v[28:31], v[138:141], v[208:211], v[28:31]
	v_mfma_f32_16x16x32_bf16 v[20:23], v[150:153], v[208:211], v[20:23]
	v_mfma_f32_16x16x32_bf16 v[12:15], v[138:141], v[234:237], v[12:15]
	v_mfma_f32_16x16x32_bf16 v[4:7], v[150:153], v[234:237], v[4:7]
	v_mfma_f32_16x16x32_bf16 v[60:63], v[146:149], v[196:199], v[60:63]
	v_mfma_f32_16x16x32_bf16 v[52:55], v[154:157], v[196:199], v[52:55]
	v_mfma_f32_16x16x32_bf16 v[44:47], v[146:149], v[204:207], v[44:47]
	v_mfma_f32_16x16x32_bf16 v[36:39], v[154:157], v[204:207], v[36:39]
	v_mfma_f32_16x16x32_bf16 v[28:31], v[146:149], v[230:233], v[28:31]
	v_mfma_f32_16x16x32_bf16 v[20:23], v[154:157], v[230:233], v[20:23]
	v_mfma_f32_16x16x32_bf16 v[12:15], v[146:149], v[238:241], v[12:15]
	v_mfma_f32_16x16x32_bf16 v[4:7], v[154:157], v[238:241], v[4:7]
	s_setprio 0
	s_setprio 1
	v_mfma_f32_16x16x32_bf16 v[56:59], v[158:161], v[192:195], v[56:59]
	v_mfma_f32_16x16x32_bf16 v[48:51], v[184:187], v[192:195], v[48:51]
	v_mfma_f32_16x16x32_bf16 v[40:43], v[158:161], v[200:203], v[40:43]
	v_mfma_f32_16x16x32_bf16 v[32:35], v[184:187], v[200:203], v[32:35]
	v_mfma_f32_16x16x32_bf16 v[24:27], v[158:161], v[208:211], v[24:27]
	v_mfma_f32_16x16x32_bf16 v[16:19], v[184:187], v[208:211], v[16:19]
	v_mfma_f32_16x16x32_bf16 v[8:11], v[158:161], v[234:237], v[8:11]
	v_mfma_f32_16x16x32_bf16 v[0:3], v[184:187], v[234:237], v[0:3]
	v_mfma_f32_16x16x32_bf16 v[56:59], v[162:165], v[196:199], v[56:59]
	v_mfma_f32_16x16x32_bf16 v[48:51], v[188:191], v[196:199], v[48:51]
	v_mfma_f32_16x16x32_bf16 v[40:43], v[162:165], v[204:207], v[40:43]
	v_mfma_f32_16x16x32_bf16 v[32:35], v[188:191], v[204:207], v[32:35]
	v_mfma_f32_16x16x32_bf16 v[24:27], v[162:165], v[230:233], v[24:27]
	v_mfma_f32_16x16x32_bf16 v[16:19], v[188:191], v[230:233], v[16:19]
	v_mfma_f32_16x16x32_bf16 v[8:11], v[162:165], v[238:241], v[8:11]
	v_mfma_f32_16x16x32_bf16 v[0:3], v[188:191], v[238:241], v[0:3]
	s_setprio 0
	s_barrier
	s_add_i32 s59, s59, 2
	s_add_u32 s34, s34, 0x100
	s_addc_u32 s35, s35, 0
	s_add_u32 s57, s57, 0x100
	s_addc_u32 s58, s58, 0
	s_cmp_gt_u32 s59, 29
	s_cbranch_scc0 .LBB0_161
	s_and_b64 vcc, exec, s[10:11]
	s_cbranch_vccz .LBB0_164
	s_barrier

; #define LAS __attribute__((address_space(3)))
; __global__ void __launch_bounds__(512, 2) fwd(Args a) {
;     extern __shared__ __attribute__((aligned(16))) unsigned char lds_[];
;     LAS unsigned char* lds = (LAS unsigned char*)lds_;
;     const int tid = threadIdx.x, lane = tid & 63, wave = __builtin_amdgcn_readfirstlane(tid >> 6);
	.amdhsa_kernel _Z3fwd4Args
		.amdhsa_group_segment_fixed_size 0
		.amdhsa_private_segment_fixed_size 0
		.amdhsa_kernarg_size 448
		.amdhsa_user_sgpr_count 2
		.amdhsa_user_sgpr_dispatch_ptr 0
		.amdhsa_user_sgpr_queue_ptr 0
		.amdhsa_user_sgpr_kernarg_segment_ptr 1
		.amdhsa_user_sgpr_dispatch_id 0
		.amdhsa_user_sgpr_kernarg_preload_length 0
		.amdhsa_user_sgpr_kernarg_preload_offset 0
		.amdhsa_user_sgpr_private_segment_size 0
		.amdhsa_uses_dynamic_stack 0
		.amdhsa_enable_private_segment 0
		.amdhsa_system_sgpr_workgroup_id_x 1
		.amdhsa_system_sgpr_workgroup_id_y 0
		.amdhsa_system_sgpr_workgroup_id_z 0
		.amdhsa_system_sgpr_workgroup_info 0
		.amdhsa_system_vgpr_workitem_id 0
		.amdhsa_next_free_vgpr 256
		.amdhsa_next_free_sgpr 102
		.amdhsa_accum_offset 256
		.amdhsa_reserve_vcc 1
		.amdhsa_float_round_mode_32 0
		.amdhsa_float_round_mode_16_64 0
		.amdhsa_float_denorm_mode_32 3
		.amdhsa_float_denorm_mode_16_64 3
		.amdhsa_dx10_clamp 1
		.amdhsa_ieee_mode 1
		.amdhsa_fp16_overflow 0
		.amdhsa_tg_split 0
		.amdhsa_exception_fp_ieee_invalid_op 0
		.amdhsa_exception_fp_denorm_src 0
		.amdhsa_exception_fp_ieee_div_zero 0
		.amdhsa_exception_fp_ieee_overflow 0
		.amdhsa_exception_fp_ieee_underflow 0
		.amdhsa_exception_fp_ieee_inexact 0
		.amdhsa_exception_int_div_zero 0
	.end_amdhsa_kernel

; __global__ void __launch_bounds__(512, 2) fwd(Args a) {
amdhsa.kernels:
  - .agpr_count:     0
    .args:
      - .offset:         0
        .size:           192
        .value_kind:     by_value
      - .offset:         192
        .size:           4
        .value_kind:     hidden_block_count_x
      - .offset:         196
        .size:           4
        .value_kind:     hidden_block_count_y
      - .offset:         200
        .size:           4
        .value_kind:     hidden_block_count_z
      - .offset:         204
        .size:           2
        .value_kind:     hidden_group_size_x
      - .offset:         206
        .size:           2
        .value_kind:     hidden_group_size_y
      - .offset:         208
        .size:           2
        .value_kind:     hidden_group_size_z
      - .offset:         210
        .size:           2
        .value_kind:     hidden_remainder_x
      - .offset:         212
        .size:           2
        .value_kind:     hidden_remainder_y
      - .offset:         214
        .size:           2
        .value_kind:     hidden_remainder_z
      - .offset:         232
        .size:           8
        .value_kind:     hidden_global_offset_x
      - .offset:         240
        .size:           8
        .value_kind:     hidden_global_offset_y
      - .offset:         248
        .size:           8
        .value_kind:     hidden_global_offset_z
      - .offset:         256
        .size:           2
        .value_kind:     hidden_grid_dims
      - .offset:         312
        .size:           4
        .value_kind:     hidden_dynamic_lds_size
    .group_segment_fixed_size: 0
    .kernarg_segment_align: 8
    .kernarg_segment_size: 448
    .language:       OpenCL C
    .language_version:
      - 2
      - 0
    .max_flat_workgroup_size: 512
    .name:           _Z3fwd4Args
    .private_segment_fixed_size: 0
    .sgpr_count:     108
    .sgpr_spill_count: 235
    .symbol:         _Z3fwd4Args.kd
    .uniform_work_group_size: 1
    .uses_dynamic_stack: false
    .vgpr_count:     256
    .vgpr_spill_count: 0
    .wavefront_size: 64
